# scan loop restructured, att-phase conv extras 3/5, FFN-up K-loop glds saddr form and 4+4 balanced staging
# baseline (speedup 1.0000x reference)
; #define PG8_WAIT_V(n) asm volatile("s_waitcnt vmcnt(" #n ")" ::: "memory")
; #define PG8_WAIT_L(n) asm volatile("s_waitcnt lgkmcnt(" #n ")" ::: "memory")
; #define PG8_BAR __builtin_amdgcn_s_barrier()
; #define PG8_SCHED __builtin_amdgcn_sched_barrier(0)
; template <class Epi, class Sched, bool ALIGN_EPI = false, bool SP2 = false, bool F8 = false>
; __device__ __forceinline__ void gemm_phase(PG8_LAS unsigned char* lds, const Gemm g, const Sched& S, const Epi& E) {
;     ...
;         for (int t = 0; t < nt; t += 2) {
;             const bool last = (t == nt - 2);
;             const char* a1 = cA + (size_t)(t + 1) * kstep;
;             const char* a2 = last ? nA : cA + (size_t)(t + 2) * kstep; const char* b2 = last ? nB : cB + (size_t)(t + 2) * kstep;
;             const char* a3 = a2 + kstep; const char* b3 = b2 + kstep;
;             if (last && has_next) S.a_ready(nxt);
;             if constexpr (SP2) {
;             PG8_LDB(B0, 0, 0); PG8_LDB(B1, 0, 1); PG8_SCHED; PG8_LDA(At, 0, 0); PG8_STAGE(PG8_SA(1, 1), a1 + hstep, voffA);
;             PG8_WAIT_V(8); PG8_WAIT_L(0); PG8_BAR; PG8_MMA(0, 0, At, B0); PG8_MMA(0, 1, At, B1); PG8_BAR; PG8_SCHED;
;             PG8_LDA(At, 0, 1); PG8_STAGE(PG8_SB(0, 0), b2, voffB); PG8_STAGE(PG8_SB(0, 1), b2 + hstep, voffB); PG8_STAGE(PG8_SA(0, 0), a2, voffA);
;             PG8_WAIT_V(8); PG8_WAIT_L(0); PG8_BAR; PG8_MMA(1, 0, At, B0); PG8_MMA(1, 1, At, B1); PG8_BAR; PG8_SCHED;
;             PG8_LDB(B0, 1, 0); PG8_LDB(B1, 1, 1); PG8_SCHED; PG8_LDA(At, 1, 0); PG8_STAGE(PG8_SA(0, 1), a2 + hstep, voffA);
;             PG8_WAIT_V(8); PG8_WAIT_L(0); PG8_BAR; PG8_MMA(0, 0, At, B0); PG8_MMA(0, 1, At, B1); PG8_BAR; PG8_SCHED;
;             PG8_LDA(At, 1, 1); PG8_STAGE(PG8_SB(1, 0), b3, voffB); PG8_STAGE(PG8_SB(1, 1), b3 + hstep, voffB); PG8_STAGE(PG8_SA(1, 0), a3, voffA);
;             PG8_WAIT_V(8); PG8_WAIT_L(0); PG8_BAR; PG8_MMA(1, 0, At, B0); PG8_MMA(1, 1, At, B1); PG8_BAR; PG8_SCHED;
.LBB0_297:
	s_add_u32 s18, s16, 0x4000
	s_addc_u32 s19, s17, 0
	s_cmp_eq_u32 s63, 28
	s_cselect_b32 s30, s59, s18
	s_cselect_b32 s31, s11, s19
	s_cselect_b32 s22, s60, s61
	s_cselect_b32 s23, s9, s62
	s_add_u32 s20, s30, 0x2000
	s_addc_u32 s21, s31, 0
	s_add_i32 s65, 0, 0x10000
	v_add_u32_e32 v145, s65, v153
	s_add_i32 s67, 0, 0x14000
	ds_read_b128 v[156:159], v145
	ds_read_b128 v[160:163], v145 offset:1024
	ds_read_b128 v[164:167], v145 offset:2048
	ds_read_b128 v[168:171], v145 offset:3072
	v_add_u32_e32 v145, s67, v153
	ds_read_b128 v[184:187], v145
	ds_read_b128 v[188:191], v145 offset:1024
	ds_read_b128 v[192:195], v145 offset:2048
	ds_read_b128 v[196:199], v145 offset:3072
	s_add_u32 s46, s16, 0x2000
	s_addc_u32 s47, s17, 0
	s_mov_b32 m0, s50
	ds_read_b128 v[200:203], v155
	ds_read_b128 v[204:207], v155 offset:1024
	ds_read_b128 v[208:211], v155 offset:2048
	ds_read_b128 v[228:231], v155 offset:3072
	ds_read_b128 v[232:235], v155 offset:4096
	ds_read_b128 v[236:239], v155 offset:5120
	ds_read_b128 v[240:243], v155 offset:6144
	ds_read_b128 v[244:247], v155 offset:7168
	global_load_lds_dwordx4 v138, s[46:47]
	s_mov_b32 m0, s52
	s_nop 0
	global_load_lds_dwordx4 v134, s[46:47]
	s_add_i32 m0, s40, 0xc000
	s_nop 0
	global_load_lds_dwordx4 v140, s[16:17]
	s_add_i32 m0, s40, 0xe000
	s_nop 0
	global_load_lds_dwordx4 v142, s[16:17]
	s_waitcnt vmcnt(8)
	s_waitcnt lgkmcnt(0)
	s_barrier
	s_setprio 1
	s_waitcnt lgkmcnt(0)
	v_mfma_f32_16x16x32_bf16 v[128:131], v[156:159], v[200:203], v[128:131]
	v_mfma_f32_16x16x32_bf16 v[124:127], v[164:167], v[200:203], v[124:127]
	v_mfma_f32_16x16x32_bf16 v[112:115], v[156:159], v[208:211], v[112:115]
	v_mfma_f32_16x16x32_bf16 v[108:111], v[164:167], v[208:211], v[108:111]
	v_mfma_f32_16x16x32_bf16 v[96:99], v[156:159], v[232:235], v[96:99]
	v_mfma_f32_16x16x32_bf16 v[92:95], v[164:167], v[232:235], v[92:95]
	v_mfma_f32_16x16x32_bf16 v[80:83], v[156:159], v[240:243], v[80:83]
	v_mfma_f32_16x16x32_bf16 v[76:79], v[164:167], v[240:243], v[76:79]
	v_mfma_f32_16x16x32_bf16 v[128:131], v[160:163], v[204:207], v[128:131]
	v_mfma_f32_16x16x32_bf16 v[124:127], v[168:171], v[204:207], v[124:127]
	v_mfma_f32_16x16x32_bf16 v[112:115], v[160:163], v[228:231], v[112:115]
	v_mfma_f32_16x16x32_bf16 v[108:111], v[168:171], v[228:231], v[108:111]
	v_mfma_f32_16x16x32_bf16 v[96:99], v[160:163], v[236:239], v[96:99]
	v_mfma_f32_16x16x32_bf16 v[92:95], v[168:171], v[236:239], v[92:95]
	v_mfma_f32_16x16x32_bf16 v[80:83], v[160:163], v[244:247], v[80:83]
	v_mfma_f32_16x16x32_bf16 v[76:79], v[168:171], v[244:247], v[76:79]
	s_setprio 0
	s_setprio 1
	v_mfma_f32_16x16x32_bf16 v[120:123], v[184:187], v[200:203], v[120:123]
	v_mfma_f32_16x16x32_bf16 v[116:119], v[192:195], v[200:203], v[116:119]
	v_mfma_f32_16x16x32_bf16 v[104:107], v[184:187], v[208:211], v[104:107]
	v_mfma_f32_16x16x32_bf16 v[100:103], v[192:195], v[208:211], v[100:103]
	v_mfma_f32_16x16x32_bf16 v[88:91], v[184:187], v[232:235], v[88:91]
	v_mfma_f32_16x16x32_bf16 v[84:87], v[192:195], v[232:235], v[84:87]
	v_mfma_f32_16x16x32_bf16 v[72:75], v[184:187], v[240:243], v[72:75]
	v_mfma_f32_16x16x32_bf16 v[68:71], v[192:195], v[240:243], v[68:71]
	v_mfma_f32_16x16x32_bf16 v[120:123], v[188:191], v[204:207], v[120:123]
	v_mfma_f32_16x16x32_bf16 v[116:119], v[196:199], v[204:207], v[116:119]
	v_mfma_f32_16x16x32_bf16 v[104:107], v[188:191], v[228:231], v[104:107]
	v_mfma_f32_16x16x32_bf16 v[100:103], v[196:199], v[228:231], v[100:103]
	v_mfma_f32_16x16x32_bf16 v[88:91], v[188:191], v[236:239], v[88:91]
	v_mfma_f32_16x16x32_bf16 v[84:87], v[196:199], v[236:239], v[84:87]
	v_mfma_f32_16x16x32_bf16 v[72:75], v[188:191], v[244:247], v[72:75]
	v_mfma_f32_16x16x32_bf16 v[68:71], v[196:199], v[244:247], v[68:71]
	s_setprio 0
	s_barrier
	s_add_i32 s16, s65, s26
	s_mov_b32 m0, s16
	ds_read_b128 v[200:203], v155 offset:16384
	ds_read_b128 v[204:207], v155 offset:17408
	ds_read_b128 v[208:211], v155 offset:18432
	ds_read_b128 v[228:231], v155 offset:19456
	ds_read_b128 v[232:235], v155 offset:20480
	ds_read_b128 v[236:239], v155 offset:21504
	ds_read_b128 v[240:243], v155 offset:22528
	ds_read_b128 v[244:247], v155 offset:23552
	global_load_lds_dwordx4 v136, s[22:23]
	s_add_i32 m0, s16, 0x2000
	s_add_u32 s16, s22, 0x80000
	s_addc_u32 s17, s23, 0
	s_add_i32 s65, s67, s26
	global_load_lds_dwordx4 v132, s[22:23]
	s_mov_b32 m0, s65
	s_nop 0
	global_load_lds_dwordx4 v136, s[16:17]
	s_add_i32 m0, s65, 0x2000
	s_nop 0
	global_load_lds_dwordx4 v132, s[16:17]
	s_waitcnt vmcnt(6)
	s_waitcnt lgkmcnt(0)
	s_barrier
; #define PG8_WAIT_V(n) asm volatile("s_waitcnt vmcnt(" #n ")" ::: "memory")
; #define PG8_WAIT_L(n) asm volatile("s_waitcnt lgkmcnt(" #n ")" ::: "memory")
; #define PG8_BAR __builtin_amdgcn_s_barrier()
; #define PG8_SCHED __builtin_amdgcn_sched_barrier(0)
; template <class Epi, class Sched, bool ALIGN_EPI = false, bool SP2 = false, bool F8 = false>
; __device__ __forceinline__ void gemm_phase(PG8_LAS unsigned char* lds, const Gemm g, const Sched& S, const Epi& E) {
;     ...
;             PG8_WAIT_V(8); PG8_WAIT_L(0); PG8_BAR; PG8_MMA(1, 0, At, B0); PG8_MMA(1, 1, At, B1); PG8_BAR; PG8_SCHED;
;             PG8_LDB(B0, 1, 0); PG8_LDB(B1, 1, 1); PG8_SCHED; PG8_LDA(At, 1, 0); PG8_STAGE(PG8_SA(0, 1), a2 + hstep, voffA);
;             PG8_WAIT_V(8); PG8_WAIT_L(0); PG8_BAR; PG8_MMA(0, 0, At, B0); PG8_MMA(0, 1, At, B1); PG8_BAR; PG8_SCHED;
	s_setprio 1
	s_waitcnt lgkmcnt(0)
	v_mfma_f32_16x16x32_bf16 v[64:67], v[156:159], v[200:203], v[64:67]
	v_mfma_f32_16x16x32_bf16 v[60:63], v[164:167], v[200:203], v[60:63]
	v_mfma_f32_16x16x32_bf16 v[48:51], v[156:159], v[208:211], v[48:51]
	v_mfma_f32_16x16x32_bf16 v[44:47], v[164:167], v[208:211], v[44:47]
	v_mfma_f32_16x16x32_bf16 v[32:35], v[156:159], v[232:235], v[32:35]
	v_mfma_f32_16x16x32_bf16 v[28:31], v[164:167], v[232:235], v[28:31]
	v_mfma_f32_16x16x32_bf16 v[16:19], v[156:159], v[240:243], v[16:19]
	v_mfma_f32_16x16x32_bf16 v[12:15], v[164:167], v[240:243], v[12:15]
	v_mfma_f32_16x16x32_bf16 v[64:67], v[160:163], v[204:207], v[64:67]
	v_mfma_f32_16x16x32_bf16 v[60:63], v[168:171], v[204:207], v[60:63]
	v_mfma_f32_16x16x32_bf16 v[48:51], v[160:163], v[228:231], v[48:51]
	v_mfma_f32_16x16x32_bf16 v[44:47], v[168:171], v[228:231], v[44:47]
	v_mfma_f32_16x16x32_bf16 v[32:35], v[160:163], v[236:239], v[32:35]
	v_mfma_f32_16x16x32_bf16 v[28:31], v[168:171], v[236:239], v[28:31]
	v_mfma_f32_16x16x32_bf16 v[16:19], v[160:163], v[244:247], v[16:19]
	v_mfma_f32_16x16x32_bf16 v[12:15], v[168:171], v[244:247], v[12:15]
	s_setprio 0
	s_setprio 1
	v_mfma_f32_16x16x32_bf16 v[56:59], v[184:187], v[200:203], v[56:59]
	v_mfma_f32_16x16x32_bf16 v[52:55], v[192:195], v[200:203], v[52:55]
	v_mfma_f32_16x16x32_bf16 v[40:43], v[184:187], v[208:211], v[40:43]
	v_mfma_f32_16x16x32_bf16 v[36:39], v[192:195], v[208:211], v[36:39]
	v_mfma_f32_16x16x32_bf16 v[24:27], v[184:187], v[232:235], v[24:27]
	v_mfma_f32_16x16x32_bf16 v[20:23], v[192:195], v[232:235], v[20:23]
	v_mfma_f32_16x16x32_bf16 v[8:11], v[184:187], v[240:243], v[8:11]
	v_mfma_f32_16x16x32_bf16 v[4:7], v[192:195], v[240:243], v[4:7]
	v_mfma_f32_16x16x32_bf16 v[56:59], v[188:191], v[204:207], v[56:59]
	v_mfma_f32_16x16x32_bf16 v[52:55], v[196:199], v[204:207], v[52:55]
	v_mfma_f32_16x16x32_bf16 v[40:43], v[188:191], v[228:231], v[40:43]
	v_mfma_f32_16x16x32_bf16 v[36:39], v[196:199], v[228:231], v[36:39]
	v_mfma_f32_16x16x32_bf16 v[24:27], v[188:191], v[236:239], v[24:27]
	v_mfma_f32_16x16x32_bf16 v[20:23], v[196:199], v[236:239], v[20:23]
	v_mfma_f32_16x16x32_bf16 v[8:11], v[188:191], v[244:247], v[8:11]
	v_mfma_f32_16x16x32_bf16 v[4:7], v[196:199], v[244:247], v[4:7]
	s_setprio 0
	s_barrier
	s_add_i32 s65, 0, 0x18000
	v_add_u32_e32 v145, s65, v153
	s_add_i32 s67, 0, 0x1c000
	ds_read_b128 v[156:159], v145
	ds_read_b128 v[160:163], v145 offset:1024
	ds_read_b128 v[164:167], v145 offset:2048
	ds_read_b128 v[168:171], v145 offset:3072
	v_add_u32_e32 v145, s67, v153
	ds_read_b128 v[184:187], v145
	ds_read_b128 v[188:191], v145 offset:1024
	ds_read_b128 v[192:195], v145 offset:2048
	ds_read_b128 v[196:199], v145 offset:3072
	s_add_u32 s16, s30, 0x80000
	s_addc_u32 s17, s31, 0
	s_mov_b32 m0, s40
	ds_read_b128 v[200:203], v155 offset:32768
	ds_read_b128 v[204:207], v155 offset:33792
	ds_read_b128 v[208:211], v155 offset:34816
	ds_read_b128 v[228:231], v155 offset:35840
	ds_read_b128 v[232:235], v155 offset:36864
	ds_read_b128 v[236:239], v155 offset:37888
	ds_read_b128 v[240:243], v155 offset:38912
	ds_read_b128 v[244:247], v155 offset:39936
	global_load_lds_dwordx4 v138, s[30:31]
	s_mov_b32 m0, s41
	s_nop 0
	global_load_lds_dwordx4 v134, s[30:31]
	s_mov_b32 m0, s42
	s_nop 0
	global_load_lds_dwordx4 v138, s[16:17]
	s_mov_b32 m0, s45
	s_nop 0
	global_load_lds_dwordx4 v134, s[16:17]
	s_waitcnt vmcnt(8)
	s_waitcnt lgkmcnt(0)
	s_barrier
; #define PG8_WAIT_V(n) asm volatile("s_waitcnt vmcnt(" #n ")" ::: "memory")
; #define PG8_WAIT_L(n) asm volatile("s_waitcnt lgkmcnt(" #n ")" ::: "memory")
; #define PG8_BAR __builtin_amdgcn_s_barrier()
; #define PG8_SCHED __builtin_amdgcn_sched_barrier(0)
; template <class Epi, class Sched, bool ALIGN_EPI = false, bool SP2 = false, bool F8 = false>
; __device__ __forceinline__ void gemm_phase(PG8_LAS unsigned char* lds, const Gemm g, const Sched& S, const Epi& E) {
;     ...
;         for (int t = 0; t < nt; t += 2) {
;             const bool last = (t == nt - 2);
;             const char* a1 = cA + (size_t)(t + 1) * kstep;
;             const char* a2 = last ? nA : cA + (size_t)(t + 2) * kstep; const char* b2 = last ? nB : cB + (size_t)(t + 2) * kstep;
;     ...
;             PG8_LDB(B0, 1, 0); PG8_LDB(B1, 1, 1); PG8_SCHED; PG8_LDA(At, 1, 0); PG8_STAGE(PG8_SA(0, 1), a2 + hstep, voffA);
;             PG8_WAIT_V(8); PG8_WAIT_L(0); PG8_BAR; PG8_MMA(0, 0, At, B0); PG8_MMA(0, 1, At, B1); PG8_BAR; PG8_SCHED;
;             PG8_LDA(At, 1, 1); PG8_STAGE(PG8_SB(1, 0), b3, voffB); PG8_STAGE(PG8_SB(1, 1), b3 + hstep, voffB); PG8_STAGE(PG8_SA(1, 0), a3, voffA);
;             PG8_WAIT_V(8); PG8_WAIT_L(0); PG8_BAR; PG8_MMA(1, 0, At, B0); PG8_MMA(1, 1, At, B1); PG8_BAR; PG8_SCHED;
	s_setprio 1
	s_waitcnt lgkmcnt(0)
	v_mfma_f32_16x16x32_bf16 v[128:131], v[156:159], v[200:203], v[128:131]
	v_mfma_f32_16x16x32_bf16 v[124:127], v[164:167], v[200:203], v[124:127]
	v_mfma_f32_16x16x32_bf16 v[112:115], v[156:159], v[208:211], v[112:115]
	v_mfma_f32_16x16x32_bf16 v[108:111], v[164:167], v[208:211], v[108:111]
	v_mfma_f32_16x16x32_bf16 v[96:99], v[156:159], v[232:235], v[96:99]
	v_mfma_f32_16x16x32_bf16 v[92:95], v[164:167], v[232:235], v[92:95]
	v_mfma_f32_16x16x32_bf16 v[80:83], v[156:159], v[240:243], v[80:83]
	v_mfma_f32_16x16x32_bf16 v[76:79], v[164:167], v[240:243], v[76:79]
	v_mfma_f32_16x16x32_bf16 v[128:131], v[160:163], v[204:207], v[128:131]
	v_mfma_f32_16x16x32_bf16 v[124:127], v[168:171], v[204:207], v[124:127]
	v_mfma_f32_16x16x32_bf16 v[112:115], v[160:163], v[228:231], v[112:115]
	v_mfma_f32_16x16x32_bf16 v[108:111], v[168:171], v[228:231], v[108:111]
	v_mfma_f32_16x16x32_bf16 v[96:99], v[160:163], v[236:239], v[96:99]
	v_mfma_f32_16x16x32_bf16 v[92:95], v[168:171], v[236:239], v[92:95]
	v_mfma_f32_16x16x32_bf16 v[80:83], v[160:163], v[244:247], v[80:83]
	v_mfma_f32_16x16x32_bf16 v[76:79], v[168:171], v[244:247], v[76:79]
	s_setprio 0
	s_setprio 1
	v_mfma_f32_16x16x32_bf16 v[120:123], v[184:187], v[200:203], v[120:123]
	v_mfma_f32_16x16x32_bf16 v[116:119], v[192:195], v[200:203], v[116:119]
	v_mfma_f32_16x16x32_bf16 v[104:107], v[184:187], v[208:211], v[104:107]
	v_mfma_f32_16x16x32_bf16 v[100:103], v[192:195], v[208:211], v[100:103]
	v_mfma_f32_16x16x32_bf16 v[88:91], v[184:187], v[232:235], v[88:91]
	v_mfma_f32_16x16x32_bf16 v[84:87], v[192:195], v[232:235], v[84:87]
	v_mfma_f32_16x16x32_bf16 v[72:75], v[184:187], v[240:243], v[72:75]
	v_mfma_f32_16x16x32_bf16 v[68:71], v[192:195], v[240:243], v[68:71]
	v_mfma_f32_16x16x32_bf16 v[120:123], v[188:191], v[204:207], v[120:123]
	v_mfma_f32_16x16x32_bf16 v[116:119], v[196:199], v[204:207], v[116:119]
	v_mfma_f32_16x16x32_bf16 v[104:107], v[188:191], v[228:231], v[104:107]
	v_mfma_f32_16x16x32_bf16 v[100:103], v[196:199], v[228:231], v[100:103]
	v_mfma_f32_16x16x32_bf16 v[88:91], v[188:191], v[236:239], v[88:91]
	v_mfma_f32_16x16x32_bf16 v[84:87], v[196:199], v[236:239], v[84:87]
	v_mfma_f32_16x16x32_bf16 v[72:75], v[188:191], v[244:247], v[72:75]
	v_mfma_f32_16x16x32_bf16 v[68:71], v[196:199], v[244:247], v[68:71]
	s_setprio 0
	s_barrier
	s_add_u32 s16, s22, 0x2000
	s_addc_u32 s17, s23, 0
	s_add_i32 s30, s65, s26
	s_mov_b32 m0, s30
	ds_read_b128 v[200:203], v155 offset:49152
	ds_read_b128 v[204:207], v155 offset:50176
	ds_read_b128 v[208:211], v155 offset:51200
	ds_read_b128 v[228:231], v155 offset:52224
	ds_read_b128 v[232:235], v155 offset:53248
	ds_read_b128 v[236:239], v155 offset:54272
	ds_read_b128 v[240:243], v155 offset:55296
	ds_read_b128 v[244:247], v155 offset:56320
	global_load_lds_dwordx4 v136, s[16:17]
	s_add_i32 m0, s30, 0x2000
	s_nop 0
	global_load_lds_dwordx4 v132, s[16:17]
	s_add_u32 s16, s22, 0x82000
	s_addc_u32 s17, s23, 0
	s_add_i32 s22, s67, s26
	s_mov_b32 m0, s22
	s_nop 0
	global_load_lds_dwordx4 v136, s[16:17]
	s_add_i32 m0, s22, 0x2000
	s_nop 0
	global_load_lds_dwordx4 v132, s[16:17]
	s_waitcnt vmcnt(6)
	s_waitcnt lgkmcnt(0)
	s_barrier
	s_setprio 1
	s_waitcnt lgkmcnt(0)
	v_mfma_f32_16x16x32_bf16 v[64:67], v[156:159], v[200:203], v[64:67]
	v_mfma_f32_16x16x32_bf16 v[60:63], v[164:167], v[200:203], v[60:63]
	v_mfma_f32_16x16x32_bf16 v[48:51], v[156:159], v[208:211], v[48:51]
	v_mfma_f32_16x16x32_bf16 v[44:47], v[164:167], v[208:211], v[44:47]
	v_mfma_f32_16x16x32_bf16 v[32:35], v[156:159], v[232:235], v[32:35]
	v_mfma_f32_16x16x32_bf16 v[28:31], v[164:167], v[232:235], v[28:31]
	v_mfma_f32_16x16x32_bf16 v[16:19], v[156:159], v[240:243], v[16:19]
	v_mfma_f32_16x16x32_bf16 v[12:15], v[164:167], v[240:243], v[12:15]
	v_mfma_f32_16x16x32_bf16 v[64:67], v[160:163], v[204:207], v[64:67]
	v_mfma_f32_16x16x32_bf16 v[60:63], v[168:171], v[204:207], v[60:63]
	v_mfma_f32_16x16x32_bf16 v[48:51], v[160:163], v[228:231], v[48:51]
	v_mfma_f32_16x16x32_bf16 v[44:47], v[168:171], v[228:231], v[44:47]
	v_mfma_f32_16x16x32_bf16 v[32:35], v[160:163], v[236:239], v[32:35]
	v_mfma_f32_16x16x32_bf16 v[28:31], v[168:171], v[236:239], v[28:31]
	v_mfma_f32_16x16x32_bf16 v[16:19], v[160:163], v[244:247], v[16:19]
	v_mfma_f32_16x16x32_bf16 v[12:15], v[168:171], v[244:247], v[12:15]
	s_setprio 0
	s_setprio 1
	v_mfma_f32_16x16x32_bf16 v[56:59], v[184:187], v[200:203], v[56:59]
	v_mfma_f32_16x16x32_bf16 v[52:55], v[192:195], v[200:203], v[52:55]
	v_mfma_f32_16x16x32_bf16 v[40:43], v[184:187], v[208:211], v[40:43]
	v_mfma_f32_16x16x32_bf16 v[36:39], v[192:195], v[208:211], v[36:39]
	v_mfma_f32_16x16x32_bf16 v[24:27], v[184:187], v[232:235], v[24:27]
	v_mfma_f32_16x16x32_bf16 v[20:23], v[192:195], v[232:235], v[20:23]
	v_mfma_f32_16x16x32_bf16 v[8:11], v[184:187], v[240:243], v[8:11]
	v_mfma_f32_16x16x32_bf16 v[4:7], v[192:195], v[240:243], v[4:7]
	v_mfma_f32_16x16x32_bf16 v[56:59], v[188:191], v[204:207], v[56:59]
	v_mfma_f32_16x16x32_bf16 v[52:55], v[196:199], v[204:207], v[52:55]
	v_mfma_f32_16x16x32_bf16 v[40:43], v[188:191], v[228:231], v[40:43]
	v_mfma_f32_16x16x32_bf16 v[36:39], v[196:199], v[228:231], v[36:39]
	v_mfma_f32_16x16x32_bf16 v[24:27], v[188:191], v[236:239], v[24:27]
	v_mfma_f32_16x16x32_bf16 v[20:23], v[196:199], v[236:239], v[20:23]
	v_mfma_f32_16x16x32_bf16 v[8:11], v[188:191], v[244:247], v[8:11]
	v_mfma_f32_16x16x32_bf16 v[4:7], v[196:199], v[244:247], v[4:7]
	s_setprio 0
	s_barrier
	s_add_i32 s63, s63, 2
	s_add_u32 s61, s61, 0x4000
	s_addc_u32 s62, s62, 0
	s_cmp_gt_u32 s63, 29
	s_mov_b64 s[16:17], s[18:19]
	s_cbranch_scc0 .LBB0_297
	s_and_b64 vcc, exec, s[6:7]
	s_cbranch_vccz .LBB0_300
	s_barrier
